# SB loops: remaining max(-z,-z)+min(120) clamp pairs merged into one v_min with the 120.0 SGPR (20 sites), on top of the per-step K/V address hoist; dead padding keeps later GEMM loops at their address
# speedup vs baseline: 1.0072x; 1.0049x over previous
; DEV void sb_block(const Params& p, int item) {
;     ...
;   for (int n = 0; n < nsteps; ++n) {
;     const int j = nsteps - 1 - n, buf = n & 3;
;     asm volatile("s_waitcnt vmcnt(8)" ::: "memory");
;     __builtin_amdgcn_s_barrier();
;     asm volatile("" ::: "memory");
;     { const int jn = j > 3 ? j - 3 : 0; SB_DMA(jn, (n + 3) & 3); }
;     const char* lb_ = smem + buf * 32768;
;     int ko0 = KO0, vo0 = VO0;
;     asm volatile("" : "+v"(ko0), "+v"(vo0));
;     if (2 * j + 1 == qt) sb_tile<true>(lb_ + 32 * 256, lb_, ko0, vo0 ^ 64, qf, O, accp, l31, hh);
;     else if (2 * j + 1 < qt) sb_tile<false>(lb_ + 32 * 256, lb_, ko0, vo0 ^ 64, qf, O, accp, l31, hh);
.LBB0_559:
	s_and_b32 s0, s33, 0x18000
	s_add_i32 s92, s0, 0
	v_add_u32_e32 v240, s92, v228
	v_add_u32_e32 v241, s92, v229
	v_add_u32_e32 v242, s92, v230
	v_add_u32_e32 v243, s92, v231
	v_add_u32_e32 v244, s92, v232
	v_add_u32_e32 v245, s92, v233
	v_add_u32_e32 v246, s92, v234
	v_add_u32_e32 v247, s92, v235
	v_add_u32_e32 v248, s92, v236
	v_add_u32_e32 v249, s92, v237
	v_add_u32_e32 v250, s92, v238
	v_add_u32_e32 v251, s92, v239
	s_add_i32 s0, s74, s69
	v_mov_b32_e32 v168, v205
	v_mov_b32_e32 v193, v206
	s_cmp_lg_u32 s89, s69
	s_mov_b64 s[66:67], -1
	s_cbranch_scc0 .LBB0_563
	s_add_i32 s1, s0, 7
	s_cmp_ge_i32 s1, s75
	s_cbranch_scc1 .Lsb_skip_A0
; DEV f32x16 mfma32(bf16x8 a, bf16x8 b, f32x16 c) { return __builtin_amdgcn_mfma_f32_32x32x16_bf16(a, b, c, 0, 0, 0); }
; template <bool DIAG>
; DEV void sb_tile(const char* lk, const char* lv, const int ko0, const int vo0, const bf16x8 (&qf)[8], f32x16 (&O)[4], float& accp,
;                  const int l31, const int hh) {
;   f32x16 z;
;   for (int g = 0; g < 16; ++g) z[g] = 0.f;
;   {
;     bf16x8 kf[8];
; #pragma unroll
;     for (int s = 0; s < 8; ++s) kf[s] = *(const bf16x8*)(lk + (ko0 ^ (32 * s)));
;     __builtin_amdgcn_sched_barrier(0);
; #pragma unroll
;     for (int s = 0; s < 8; ++s) z = mfma32(kf[s], qf[s], z);
;   }
;   bf16x8 vf[4][2];
; #pragma unroll
;   for (int d = 0; d < 4; ++d) { vf[d][0] = *(const bf16x8*)(lv + d * 4096 + vo0); vf[d][1] = *(const bf16x8*)(lv + d * 4096 + (vo0 ^ 32)); }
;   __builtin_amdgcn_sched_barrier(0);
;   float be[16], om[16];
; #pragma unroll
;   for (int g = 0; g < 16; ++g) {
;     const float e = __builtin_amdgcn_exp2f(fminf(-z[g], 120.f));
;     be[g] = __builtin_amdgcn_rcpf(1.f + e);
;     om[g] = e * be[g];
;     if (DIAG) { const int kl = (g & 3) + 8 * (g >> 2) + 4 * hh; if (kl >= l31) { be[g] = 0.f; om[g] = 1.f; } }
;   }
;   float gp[4], pp[4], tot[4];
; #pragma unroll
;   for (int q = 0; q < 4; ++q) { gp[q] = (om[4 * q] * om[4 * q + 1]) * (om[4 * q + 2] * om[4 * q + 3]); pp[q] = __shfl_xor(gp[q], 32); tot[q] = gp[q] * pp[q]; }
;   float suf[4];
;   suf[3] = accp; suf[2] = suf[3] * tot[3]; suf[1] = suf[2] * tot[2]; suf[0] = suf[1] * tot[1];
;   accp = suf[0] * tot[0];
;   f32x16 w;
; #pragma unroll
;   for (int q = 0; q < 4; ++q) {
;     float a = suf[q] * (hh == 0 ? pp[q] : 1.f);
;     w[4 * q + 3] = be[4 * q + 3] * a; a *= om[4 * q + 3];
;     w[4 * q + 2] = be[4 * q + 2] * a; a *= om[4 * q + 2];
;     w[4 * q + 1] = be[4 * q + 1] * a; a *= om[4 * q + 1];
;     w[4 * q + 0] = be[4 * q + 0] * a;
;   }
;   const bf16x8 w0 = cvt8<0>(w), w1 = cvt8<1>(w);
; #pragma unroll
;   for (int d = 0; d < 4; ++d) { O[d] = mfma32(vf[d][0], w0, O[d]); O[d] = mfma32(vf[d][1], w1, O[d]); }
	ds_read_b128 v[64:67], v240 offset:8192
	ds_read_b128 v[80:83], v241 offset:8192
	ds_read_b128 v[84:87], v242 offset:8192
	ds_read_b128 v[88:91], v243 offset:8192
	ds_read_b128 v[92:95], v244 offset:8192
	ds_read_b128 v[96:99], v245 offset:8192
	ds_read_b128 v[100:103], v246 offset:8192
	ds_read_b128 v[104:107], v247 offset:8192
	s_waitcnt lgkmcnt(0)
	v_mfma_f32_32x32x16_bf16 v[64:79], v[64:67], v[128:131], 0
	v_mfma_f32_32x32x16_bf16 v[64:79], v[80:83], v[132:135], v[64:79]
	v_mfma_f32_32x32x16_bf16 v[64:79], v[84:87], v[136:139], v[64:79]
	v_mfma_f32_32x32x16_bf16 v[64:79], v[88:91], v[140:143], v[64:79]
	v_mfma_f32_32x32x16_bf16 v[64:79], v[92:95], v[144:147], v[64:79]
	v_mfma_f32_32x32x16_bf16 v[64:79], v[96:99], v[148:151], v[64:79]
	v_mfma_f32_32x32x16_bf16 v[64:79], v[100:103], v[152:155], v[64:79]
	ds_read_b128 v[84:87], v250
	ds_read_b128 v[96:99], v250 offset:4096
	ds_read_b128 v[80:83], v251
	ds_read_b128 v[100:103], v251 offset:4096
	ds_read_b128 v[112:115], v250 offset:8192
	ds_read_b128 v[164:167], v250 offset:12288
	ds_read_b128 v[116:119], v251 offset:8192
	ds_read_b128 v[160:163], v251 offset:12288
	v_mfma_f32_32x32x16_bf16 v[64:79], v[104:107], v[156:159], v[64:79]
	s_nop 11
	v_min_f32_e64 v68, -v68, s32
	v_exp_f32_e32 v90, v68
	v_min_f32_e64 v68, -v69, s32
	v_exp_f32_e32 v91, v68
	v_add_f32_e32 v68, 1.0, v90
	v_min_f32_e64 v73, -v73, s32
	v_add_f32_e32 v69, 1.0, v91
	v_rcp_f32_e32 v68, v68
	v_rcp_f32_e32 v69, v69
	v_exp_f32_e32 v104, v73
	v_min_f32_e64 v73, -v74, s32
	v_min_f32_e64 v74, -v75, s32
	v_min_f32_e64 v72, -v72, s32
	v_min_f32_e64 v75, -v77, s32
	v_min_f32_e64 v77, -v79, s32
	v_and_b32_e32 v79, 64, v219
	v_exp_f32_e32 v72, v72
	v_exp_f32_e32 v105, v74
	v_min_f32_e64 v74, -v76, s32
	v_exp_f32_e32 v76, v75
	v_min_f32_e64 v75, -v78, s32
	v_xor_b32_e32 v78, 32, v219
	v_add_u32_e32 v79, 64, v79
	v_cmp_lt_i32_e32 vcc, v78, v79
	v_pk_mul_f32 v[90:91], v[90:91], v[68:69]
	v_exp_f32_e32 v73, v73
	v_cndmask_b32_e32 v78, v219, v78, vcc
	v_lshlrev_b32_e32 v170, 2, v78
	v_pk_mul_f32 v[78:79], v[90:91], v[90:91] op_sel_hi:[0,1]
	v_add_f32_e32 v78, 1.0, v72
	v_rcp_f32_e32 v108, v78
	v_add_f32_e32 v78, 1.0, v104
	v_rcp_f32_e32 v110, v78
	v_add_f32_e32 v78, 1.0, v73
	v_rcp_f32_e32 v109, v78
	v_add_f32_e32 v78, 1.0, v105
	v_rcp_f32_e32 v111, v78
	v_exp_f32_e32 v74, v74
	v_exp_f32_e32 v75, v75
	v_exp_f32_e32 v77, v77
	v_pk_mul_f32 v[72:73], v[72:73], v[108:109]
	v_pk_mul_f32 v[104:105], v[104:105], v[110:111]
	v_pk_mul_f32 v[120:121], v[72:73], v[104:105]
	v_add_f32_e32 v72, 1.0, v74
	v_rcp_f32_e32 v122, v72
	v_add_f32_e32 v72, 1.0, v76
	v_rcp_f32_e32 v124, v72
	v_add_f32_e32 v72, 1.0, v75
	v_min_f32_e64 v70, -v70, s32
	v_rcp_f32_e32 v123, v72
	v_add_f32_e32 v72, 1.0, v77
	v_exp_f32_e32 v92, v70
	v_rcp_f32_e32 v125, v72
	v_min_f32_e64 v70, -v71, s32
	v_min_f32_e64 v67, -v67, s32
	v_exp_f32_e32 v93, v70
	v_min_f32_e64 v64, -v64, s32
	v_exp_f32_e32 v196, v67
	v_exp_f32_e32 v88, v64
	v_pk_mul_f32 v[74:75], v[74:75], v[122:123]
	v_pk_mul_f32 v[76:77], v[76:77], v[124:125]
	v_add_f32_e32 v70, 1.0, v92
	v_pk_mul_f32 v[126:127], v[74:75], v[76:77]
	v_add_f32_e32 v71, 1.0, v93
	v_mul_f32_e32 v72, v126, v127
	v_add_f32_e32 v67, 1.0, v196
	v_rcp_f32_e32 v70, v70
	v_rcp_f32_e32 v71, v71
	v_pk_mul_f32 v[120:121], v[120:121], v[120:121] op_sel:[0,1] op_sel_hi:[1,0]
	v_mov_b32_e32 v74, v72
	s_nop 1
	v_permlane32_swap_b32_e32 v72, v74
	v_add_f32_e32 v64, 1.0, v88
	v_min_f32_e64 v66, -v66, s32
	v_rcp_f32_e32 v67, v67
	v_mov_b32_e32 v121, v120
	s_nop 1
	v_permlane32_swap_b32_e32 v120, v121
	v_rcp_f32_e32 v64, v64
	v_min_f32_e64 v65, -v65, s32
	v_exp_f32_e32 v94, v66
	v_exp_f32_e32 v169, v65
	v_pk_mul_f32 v[92:93], v[92:93], v[70:71]
	s_waitcnt lgkmcnt(0)
	v_mul_f32_e32 v127, v72, v74
	v_pk_mul_f32 v[106:107], v[92:93], v[92:93] op_sel_hi:[0,1]
	v_mov_b32_e32 v126, v67
	v_add_f32_e32 v66, 1.0, v94
	v_mov_b32_e32 v89, v79
	v_cndmask_b32_e64 v72, 1.0, v121, s[10:11]
	v_mov_b32_e32 v78, v109
	v_mov_b32_e32 v79, v111
	v_mov_b32_e32 v109, v110
	v_pk_mul_f32 v[110:111], v[196:197], v[126:127]
	v_mov_b32_e32 v106, v64
	v_add_f32_e32 v65, 1.0, v169
	v_rcp_f32_e32 v66, v66
	v_mul_f32_e32 v127, v72, v111
	v_pk_mul_f32 v[88:89], v[88:89], v[106:107]
	v_rcp_f32_e32 v65, v65
	v_mul_f32_e32 v126, v105, v127
	v_mov_b32_e32 v105, v89
	s_nop 1
	v_permlane32_swap_b32_e32 v89, v105
	v_mov_b32_e32 v95, v120
	v_mov_b32_e32 v120, v66
	v_mul_f32_e32 v73, v73, v126
	v_pk_mul_f32 v[94:95], v[94:95], v[120:121]
	v_mul_f32_e32 v72, v104, v73
	v_mul_f32_e32 v104, v169, v65
	v_pk_mul_f32 v[120:121], v[94:95], v[110:111]
	s_waitcnt lgkmcnt(0)
	v_pk_mul_f32 v[88:89], v[88:89], v[104:105]
	v_cndmask_b32_e64 v90, 1.0, v105, s[10:11]
	v_pk_mul_f32 v[88:89], v[88:89], v[120:121]
	v_mov_b32_e32 v95, v88
	s_nop 1
	v_permlane32_swap_b32_e32 v88, v95
	v_cndmask_b32_e64 v74, 1.0, v74, s[10:11]
	v_pk_mul_f32 v[78:79], v[78:79], v[126:127]
	v_pk_mul_f32 v[72:73], v[108:109], v[72:73]
	v_cvt_pk_bf16_f32 v209, v78, v79
	s_waitcnt lgkmcnt(0)
	v_mul_f32_e32 v88, v88, v95
	v_mul_f32_e32 v199, v88, v89
	v_cndmask_b32_e64 v88, 1.0, v95, s[10:11]
	v_mul_f32_e32 v89, v88, v89
	v_mul_f32_e32 v88, v110, v89
	v_pk_mul_f32 v[66:67], v[66:67], v[88:89]
	v_mul_f32_e32 v89, v90, v121
	v_mul_f32_e32 v95, v94, v88
	v_mul_f32_e32 v88, v93, v89
	v_mul_f32_e32 v93, v92, v88
	v_mul_f32_e32 v92, v91, v93
	v_mul_f32_e32 v91, v197, v74
	v_mul_f32_e32 v90, v77, v91
	v_mul_f32_e32 v94, v104, v95
	v_mul_f32_e32 v75, v75, v90
	v_pk_mul_f32 v[64:65], v[64:65], v[94:95]
	v_pk_mul_f32 v[68:69], v[68:69], v[92:93]
	v_pk_mul_f32 v[70:71], v[70:71], v[88:89]
	v_mov_b32_e32 v88, v123
	v_mov_b32_e32 v123, v124
	v_mul_f32_e32 v74, v76, v75
	v_pk_mul_f32 v[74:75], v[122:123], v[74:75]
	v_cvt_pk_bf16_f32 v170, v64, v65
	v_cvt_pk_bf16_f32 v171, v66, v67
	v_cvt_pk_bf16_f32 v172, v68, v69
	v_cvt_pk_bf16_f32 v173, v70, v71
	v_cvt_pk_bf16_f32 v208, v72, v73
	v_cvt_pk_bf16_f32 v210, v74, v75
	v_mfma_f32_32x32x16_bf16 v[64:79], v[84:87], v[170:173], v[48:63]
	v_mov_b32_e32 v89, v125
	v_mul_f32_e64 v88, v88, v90
	v_mul_f32_e64 v89, v89, v91
	v_cvt_pk_bf16_f32 v211, v88, v89
	s_nop 1
	v_mfma_f32_32x32x16_bf16 v[64:79], v[80:83], v[208:211], v[64:79]
	v_mfma_f32_32x32x16_bf16 v[80:95], v[96:99], v[170:173], v[32:47]
	v_mfma_f32_32x32x16_bf16 v[80:95], v[100:103], v[208:211], v[80:95]
	v_mfma_f32_32x32x16_bf16 v[96:111], v[112:115], v[170:173], v[16:31]
	v_mfma_f32_32x32x16_bf16 v[96:111], v[116:119], v[208:211], v[96:111]
	v_mfma_f32_32x32x16_bf16 v[112:127], v[164:167], v[170:173], v[0:15]
	v_mfma_f32_32x32x16_bf16 v[112:127], v[160:163], v[208:211], v[112:127]

; DEV f32x16 mfma32(bf16x8 a, bf16x8 b, f32x16 c) { return __builtin_amdgcn_mfma_f32_32x32x16_bf16(a, b, c, 0, 0, 0); }
; template <bool DIAG>
; DEV void sb_tile(const char* lk, const char* lv, const int ko0, const int vo0, const bf16x8 (&qf)[8], f32x16 (&O)[4], float& accp,
;                  const int l31, const int hh) {
;   f32x16 z;
;   for (int g = 0; g < 16; ++g) z[g] = 0.f;
;   {
;     bf16x8 kf[8];
; #pragma unroll
;     for (int s = 0; s < 8; ++s) kf[s] = *(const bf16x8*)(lk + (ko0 ^ (32 * s)));
;     __builtin_amdgcn_sched_barrier(0);
; #pragma unroll
;     for (int s = 0; s < 8; ++s) z = mfma32(kf[s], qf[s], z);
;   }
;   bf16x8 vf[4][2];
; #pragma unroll
;   for (int d = 0; d < 4; ++d) { vf[d][0] = *(const bf16x8*)(lv + d * 4096 + vo0); vf[d][1] = *(const bf16x8*)(lv + d * 4096 + (vo0 ^ 32)); }
;   __builtin_amdgcn_sched_barrier(0);
;   float be[16], om[16];
; #pragma unroll
;   for (int g = 0; g < 16; ++g) {
;     const float e = __builtin_amdgcn_exp2f(fminf(-z[g], 120.f));
;     be[g] = __builtin_amdgcn_rcpf(1.f + e);
;     om[g] = e * be[g];
;     if (DIAG) { const int kl = (g & 3) + 8 * (g >> 2) + 4 * hh; if (kl >= l31) { be[g] = 0.f; om[g] = 1.f; } }
;   }
;   float gp[4], pp[4], tot[4];
; #pragma unroll
;   for (int q = 0; q < 4; ++q) { gp[q] = (om[4 * q] * om[4 * q + 1]) * (om[4 * q + 2] * om[4 * q + 3]); pp[q] = __shfl_xor(gp[q], 32); tot[q] = gp[q] * pp[q]; }
;   float suf[4];
;   suf[3] = accp; suf[2] = suf[3] * tot[3]; suf[1] = suf[2] * tot[2]; suf[0] = suf[1] * tot[1];
;   accp = suf[0] * tot[0];
;   f32x16 w;
; #pragma unroll
;   for (int q = 0; q < 4; ++q) {
;     float a = suf[q] * (hh == 0 ? pp[q] : 1.f);
;     w[4 * q + 3] = be[4 * q + 3] * a; a *= om[4 * q + 3];
;     w[4 * q + 2] = be[4 * q + 2] * a; a *= om[4 * q + 2];
;     w[4 * q + 1] = be[4 * q + 1] * a; a *= om[4 * q + 1];
;     w[4 * q + 0] = be[4 * q + 0] * a;
;   }
;   const bf16x8 w0 = cvt8<0>(w), w1 = cvt8<1>(w);
; #pragma unroll
;   for (int d = 0; d < 4; ++d) { O[d] = mfma32(vf[d][0], w0, O[d]); O[d] = mfma32(vf[d][1], w1, O[d]); }
; DEV void sb_block(const Params& p, int item) {
;     ...
;     if (2 * j == qt) sb_tile<true>(lb_, lb_, ko0, vo0, qf, O, accp, l31, hh);
;     else if (2 * j < qt) sb_tile<false>(lb_, lb_, ko0, vo0, qf, O, accp, l31, hh);
.LBB0_565:
	s_cmp_lg_u32 s88, s69
	s_mov_b64 s[66:67], -1
	s_cbranch_scc0 .LBB0_569
	s_add_i32 s0, s0, 6
	s_cmp_ge_i32 s0, s75
	s_cbranch_scc1 .Lsb_skip_B0
	ds_read_b128 v[0:3], v240
	ds_read_b128 v[16:19], v241
	ds_read_b128 v[20:23], v242
	ds_read_b128 v[24:27], v243
	ds_read_b128 v[28:31], v244
	ds_read_b128 v[32:35], v245
	ds_read_b128 v[36:39], v246
	ds_read_b128 v[40:43], v247
	s_waitcnt lgkmcnt(0)
	v_mfma_f32_32x32x16_bf16 v[0:15], v[0:3], v[128:131], 0
	v_mfma_f32_32x32x16_bf16 v[0:15], v[16:19], v[132:135], v[0:15]
	v_mfma_f32_32x32x16_bf16 v[0:15], v[20:23], v[136:139], v[0:15]
	v_mfma_f32_32x32x16_bf16 v[0:15], v[24:27], v[140:143], v[0:15]
	v_mfma_f32_32x32x16_bf16 v[0:15], v[28:31], v[144:147], v[0:15]
	v_mfma_f32_32x32x16_bf16 v[0:15], v[32:35], v[148:151], v[0:15]
	ds_read_b128 v[28:31], v248
	ds_read_b128 v[16:19], v248 offset:4096
	ds_read_b128 v[24:27], v249
	ds_read_b128 v[20:23], v249 offset:4096
	ds_read_b128 v[168:171], v248 offset:8192
	ds_read_b128 v[164:167], v248 offset:12288
	ds_read_b128 v[172:175], v249 offset:8192
	ds_read_b128 v[160:163], v249 offset:12288
	v_mfma_f32_32x32x16_bf16 v[0:15], v[36:39], v[152:155], v[0:15]
	v_mfma_f32_32x32x16_bf16 v[0:15], v[40:43], v[156:159], v[0:15]
	s_nop 11
	v_min_f32_e64 v4, -v4, s32
	v_exp_f32_e32 v34, v4
	v_min_f32_e64 v4, -v5, s32
	v_exp_f32_e32 v35, v4
	v_add_f32_e32 v4, 1.0, v34
	v_min_f32_e64 v9, -v9, s32
	v_add_f32_e32 v5, 1.0, v35
	v_rcp_f32_e32 v4, v4
	v_rcp_f32_e32 v5, v5
	v_exp_f32_e32 v40, v9
	v_min_f32_e64 v9, -v10, s32
	v_min_f32_e64 v10, -v11, s32
	v_min_f32_e64 v8, -v8, s32
	v_min_f32_e64 v11, -v13, s32
	v_min_f32_e64 v13, -v15, s32
	v_and_b32_e32 v15, 64, v219
	v_exp_f32_e32 v8, v8
	v_exp_f32_e32 v41, v10
	v_min_f32_e64 v10, -v12, s32
	v_exp_f32_e32 v12, v11
	v_min_f32_e64 v11, -v14, s32
	v_xor_b32_e32 v14, 32, v219
	v_add_u32_e32 v15, 64, v15
	v_cmp_lt_i32_e32 vcc, v14, v15
	v_pk_mul_f32 v[34:35], v[34:35], v[4:5]
	v_exp_f32_e32 v9, v9
	v_cndmask_b32_e32 v14, v219, v14, vcc
	v_lshlrev_b32_e32 v57, 2, v14
	v_pk_mul_f32 v[14:15], v[34:35], v[34:35] op_sel_hi:[0,1]
	v_add_f32_e32 v14, 1.0, v8
	v_rcp_f32_e32 v44, v14
	v_add_f32_e32 v14, 1.0, v40
	v_rcp_f32_e32 v46, v14
	v_add_f32_e32 v14, 1.0, v9
	v_rcp_f32_e32 v45, v14
	v_add_f32_e32 v14, 1.0, v41
	v_rcp_f32_e32 v47, v14
	v_exp_f32_e32 v10, v10
	v_exp_f32_e32 v11, v11
	v_exp_f32_e32 v13, v13
	v_pk_mul_f32 v[8:9], v[8:9], v[44:45]
	v_pk_mul_f32 v[40:41], v[40:41], v[46:47]
	v_pk_mul_f32 v[48:49], v[8:9], v[40:41]
	v_add_f32_e32 v8, 1.0, v10
	v_rcp_f32_e32 v50, v8
	v_add_f32_e32 v8, 1.0, v12
	v_rcp_f32_e32 v52, v8
	v_add_f32_e32 v8, 1.0, v11
	v_min_f32_e64 v6, -v6, s32
	v_rcp_f32_e32 v51, v8
	v_add_f32_e32 v8, 1.0, v13
	v_exp_f32_e32 v36, v6
	v_rcp_f32_e32 v53, v8
	v_min_f32_e64 v6, -v7, s32
	v_min_f32_e64 v3, -v3, s32
	v_exp_f32_e32 v37, v6
	v_min_f32_e64 v0, -v0, s32
	v_exp_f32_e32 v198, v3
	v_exp_f32_e32 v32, v0
	v_pk_mul_f32 v[10:11], v[10:11], v[50:51]
	v_pk_mul_f32 v[12:13], v[12:13], v[52:53]
	v_add_f32_e32 v6, 1.0, v36
	v_pk_mul_f32 v[54:55], v[10:11], v[12:13]
	v_add_f32_e32 v7, 1.0, v37
	v_mul_f32_e32 v8, v54, v55
	v_add_f32_e32 v3, 1.0, v198
	v_rcp_f32_e32 v6, v6
	v_rcp_f32_e32 v7, v7
	v_pk_mul_f32 v[48:49], v[48:49], v[48:49] op_sel:[0,1] op_sel_hi:[1,0]
	v_mov_b32_e32 v10, v8
	s_nop 1
	v_permlane32_swap_b32_e32 v8, v10
	v_add_f32_e32 v0, 1.0, v32
	v_min_f32_e64 v2, -v2, s32
	v_rcp_f32_e32 v3, v3
	v_mov_b32_e32 v49, v48
	s_nop 1
	v_permlane32_swap_b32_e32 v48, v49
	v_rcp_f32_e32 v0, v0
	v_min_f32_e64 v1, -v1, s32
	v_exp_f32_e32 v38, v2
	v_exp_f32_e32 v56, v1
	v_pk_mul_f32 v[36:37], v[36:37], v[6:7]
	s_waitcnt lgkmcnt(0)
	v_mul_f32_e32 v55, v8, v10
	v_pk_mul_f32 v[42:43], v[36:37], v[36:37] op_sel_hi:[0,1]
	v_mov_b32_e32 v54, v3
	v_add_f32_e32 v2, 1.0, v38
	v_mov_b32_e32 v33, v15
	v_cndmask_b32_e64 v8, 1.0, v49, s[10:11]
	v_mov_b32_e32 v14, v45
	v_mov_b32_e32 v15, v47
	v_mov_b32_e32 v45, v46
	v_pk_mul_f32 v[46:47], v[198:199], v[54:55]
	v_mov_b32_e32 v42, v0
	v_add_f32_e32 v1, 1.0, v56
	v_rcp_f32_e32 v2, v2
	v_mul_f32_e32 v55, v8, v47
	v_pk_mul_f32 v[32:33], v[32:33], v[42:43]
	v_rcp_f32_e32 v1, v1
	v_mul_f32_e32 v54, v41, v55
	v_mov_b32_e32 v41, v33
	s_nop 1
	v_permlane32_swap_b32_e32 v33, v41
	v_mov_b32_e32 v39, v48
	v_mov_b32_e32 v48, v2
	v_mul_f32_e32 v9, v9, v54
	v_pk_mul_f32 v[38:39], v[38:39], v[48:49]
	v_mul_f32_e32 v8, v40, v9
	v_mul_f32_e32 v40, v56, v1
	v_pk_mul_f32 v[48:49], v[38:39], v[46:47]
	s_waitcnt lgkmcnt(0)
	v_pk_mul_f32 v[32:33], v[32:33], v[40:41]
	v_cndmask_b32_e64 v34, 1.0, v41, s[10:11]
	v_pk_mul_f32 v[32:33], v[32:33], v[48:49]
	v_mov_b32_e32 v39, v32
	s_nop 1
	v_permlane32_swap_b32_e32 v32, v39
	v_cndmask_b32_e64 v10, 1.0, v10, s[10:11]
	v_pk_mul_f32 v[14:15], v[14:15], v[54:55]
	v_pk_mul_f32 v[8:9], v[44:45], v[8:9]
	v_cvt_pk_bf16_f32 v225, v14, v15
	s_waitcnt lgkmcnt(0)
	v_mul_f32_e32 v32, v32, v39
	v_mul_f32_e32 v197, v32, v33
	v_cndmask_b32_e64 v32, 1.0, v39, s[10:11]
	v_mul_f32_e32 v33, v32, v33
	v_mul_f32_e32 v32, v46, v33
	v_pk_mul_f32 v[2:3], v[2:3], v[32:33]
	v_mul_f32_e32 v33, v34, v49
	v_mul_f32_e32 v39, v38, v32
	v_mul_f32_e32 v32, v37, v33
	v_mul_f32_e32 v37, v36, v32
	v_mul_f32_e32 v36, v35, v37
	v_mul_f32_e32 v35, v199, v10
	v_mul_f32_e32 v38, v40, v39
	v_mul_f32_e32 v34, v13, v35
	v_pk_mul_f32 v[0:1], v[0:1], v[38:39]
	v_pk_mul_f32 v[4:5], v[4:5], v[36:37]
	v_pk_mul_f32 v[6:7], v[6:7], v[32:33]
	v_mov_b32_e32 v32, v51
	v_mov_b32_e32 v33, v53
	v_mul_f32_e32 v11, v11, v34
	v_pk_mul_f32 v[32:33], v[32:33], v[34:35]
	v_mov_b32_e32 v51, v52
	v_mul_f32_e32 v10, v12, v11
	v_cvt_pk_bf16_f32 v214, v0, v1
	v_cvt_pk_bf16_f32 v215, v2, v3
	v_cvt_pk_bf16_f32 v216, v4, v5
	v_cvt_pk_bf16_f32 v217, v6, v7
	v_pk_mul_f32 v[10:11], v[50:51], v[10:11]
	v_cvt_pk_bf16_f32 v227, v32, v33
	v_mfma_f32_32x32x16_bf16 v[48:63], v[28:31], v[214:217], v[64:79]
	v_cvt_pk_bf16_f32 v224, v8, v9
	v_cvt_pk_bf16_f32 v226, v10, v11
	v_mfma_f32_32x32x16_bf16 v[32:47], v[16:19], v[214:217], v[80:95]
	s_nop 0
	v_mfma_f32_32x32x16_bf16 v[48:63], v[24:27], v[224:227], v[48:63]
	v_mfma_f32_32x32x16_bf16 v[32:47], v[20:23], v[224:227], v[32:47]
	v_mfma_f32_32x32x16_bf16 v[16:31], v[168:171], v[214:217], v[96:111]
	v_mfma_f32_32x32x16_bf16 v[0:15], v[164:167], v[214:217], v[112:127]
	v_mfma_f32_32x32x16_bf16 v[16:31], v[172:175], v[224:227], v[16:31]
	v_mfma_f32_32x32x16_bf16 v[0:15], v[160:163], v[224:227], v[0:15]

; DEV void sb_block(const Params& p, int item) {
;     ...
;   for (int n = 0; n < nsteps; ++n) {
;     const int j = nsteps - 1 - n, buf = n & 3;
;     asm volatile("s_waitcnt vmcnt(8)" ::: "memory");
;     __builtin_amdgcn_s_barrier();
;     asm volatile("" ::: "memory");
;     { const int jn = j > 3 ? j - 3 : 0; SB_DMA(jn, (n + 3) & 3); }
;     const char* lb_ = smem + buf * 32768;
;     int ko0 = KO0, vo0 = VO0;
;     asm volatile("" : "+v"(ko0), "+v"(vo0));
;     if (2 * j + 1 == qt) sb_tile<true>(lb_ + 32 * 256, lb_, ko0, vo0 ^ 64, qf, O, accp, l31, hh);
;     else if (2 * j + 1 < qt) sb_tile<false>(lb_ + 32 * 256, lb_, ko0, vo0 ^ 64, qf, O, accp, l31, hh);
;     if (2 * j == qt) sb_tile<true>(lb_, lb_, ko0, vo0, qf, O, accp, l31, hh);
;     else if (2 * j < qt) sb_tile<false>(lb_, lb_, ko0, vo0, qf, O, accp, l31, hh);
;     asm volatile("" ::: "memory");
;   }
.Lsb_skip_A0:
	v_mov_b64_e32 v[78:79], v[62:63]
	v_mov_b64_e32 v[94:95], v[46:47]
	v_mov_b64_e32 v[110:111], v[30:31]
	v_mov_b64_e32 v[126:127], v[14:15]
	v_mov_b32_e32 v199, v197
	v_mov_b64_e32 v[76:77], v[60:61]
	v_mov_b64_e32 v[74:75], v[58:59]
	v_mov_b64_e32 v[72:73], v[56:57]
	v_mov_b64_e32 v[70:71], v[54:55]
	v_mov_b64_e32 v[68:69], v[52:53]
	v_mov_b64_e32 v[66:67], v[50:51]
	v_mov_b64_e32 v[64:65], v[48:49]
	v_mov_b64_e32 v[92:93], v[44:45]
	v_mov_b64_e32 v[90:91], v[42:43]
	v_mov_b64_e32 v[88:89], v[40:41]
	v_mov_b64_e32 v[86:87], v[38:39]
	v_mov_b64_e32 v[84:85], v[36:37]
	v_mov_b64_e32 v[82:83], v[34:35]
	v_mov_b64_e32 v[80:81], v[32:33]
	v_mov_b64_e32 v[108:109], v[28:29]
	v_mov_b64_e32 v[106:107], v[26:27]
	v_mov_b64_e32 v[104:105], v[24:25]
	v_mov_b64_e32 v[102:103], v[22:23]
	v_mov_b64_e32 v[100:101], v[20:21]
	v_mov_b64_e32 v[98:99], v[18:19]
	v_mov_b64_e32 v[96:97], v[16:17]
	v_mov_b64_e32 v[124:125], v[12:13]
	v_mov_b64_e32 v[122:123], v[10:11]
	v_mov_b64_e32 v[120:121], v[8:9]
	v_mov_b64_e32 v[118:119], v[6:7]
	v_mov_b64_e32 v[116:117], v[4:5]
	v_mov_b64_e32 v[114:115], v[2:3]
	v_mov_b64_e32 v[112:113], v[0:1]
	s_branch .LBB0_562
	s_nop 0
	s_nop 0
	s_nop 0
	s_nop 0
	s_nop 0
	s_nop 0
	s_nop 0
	s_nop 0
	s_nop 0
	s_nop 0
	s_nop 0
	s_nop 0
	s_nop 0
	s_nop 0
	s_nop 0
	s_nop 0
	s_nop 0
	s_nop 0
	s_nop 0
	s_nop 0
	s_nop 0
	s_nop 0
	s_nop 0
	s_nop 0
	s_nop 0
	s_nop 0
	s_nop 0
	s_nop 0
	s_nop 0
	s_nop 0
	s_nop 0
	s_nop 0
	s_nop 0
	s_nop 0
	s_nop 0
	s_nop 0
	s_nop 0
	s_nop 0
	s_nop 0
	s_nop 0
	s_nop 0
	s_nop 0
	s_nop 0
	s_nop 0
	s_nop 0
	s_nop 0

; DEV void sb_block(const Params& p, int item) {
;     ...
;   for (int n = 0; n < nsteps; ++n) {
;     const int j = nsteps - 1 - n, buf = n & 3;
;     asm volatile("s_waitcnt vmcnt(8)" ::: "memory");
;     __builtin_amdgcn_s_barrier();
;     asm volatile("" ::: "memory");
;     { const int jn = j > 3 ? j - 3 : 0; SB_DMA(jn, (n + 3) & 3); }
;     const char* lb_ = smem + buf * 32768;
;     int ko0 = KO0, vo0 = VO0;
;     asm volatile("" : "+v"(ko0), "+v"(vo0));
;     if (2 * j + 1 == qt) sb_tile<true>(lb_ + 32 * 256, lb_, ko0, vo0 ^ 64, qf, O, accp, l31, hh);
;     else if (2 * j + 1 < qt) sb_tile<false>(lb_ + 32 * 256, lb_, ko0, vo0 ^ 64, qf, O, accp, l31, hh);
.LBB0_1211:
	s_and_b32 s66, s33, 0x18000
	s_add_i32 s92, s66, 0
	v_add_u32_e32 v240, s92, v228
	v_add_u32_e32 v241, s92, v229
	v_add_u32_e32 v242, s92, v230
	v_add_u32_e32 v243, s92, v231
	v_add_u32_e32 v244, s92, v232
	v_add_u32_e32 v245, s92, v233
	v_add_u32_e32 v246, s92, v234
	v_add_u32_e32 v247, s92, v235
	v_add_u32_e32 v248, s92, v236
	v_add_u32_e32 v249, s92, v237
	v_add_u32_e32 v250, s92, v238
	v_add_u32_e32 v251, s92, v239
	s_add_i32 s90, s74, s69
	v_mov_b32_e32 v168, v205
	v_mov_b32_e32 v193, v206
	s_cmp_lg_u32 s89, s69
	s_mov_b64 s[66:67], -1
	s_cbranch_scc0 .LBB0_1215
	s_add_i32 s66, s90, 7
	s_cmp_ge_i32 s66, s76
	s_cbranch_scc1 .Lsb_skip_A1
; DEV f32x16 mfma32(bf16x8 a, bf16x8 b, f32x16 c) { return __builtin_amdgcn_mfma_f32_32x32x16_bf16(a, b, c, 0, 0, 0); }
; template <bool DIAG>
; DEV void sb_tile(const char* lk, const char* lv, const int ko0, const int vo0, const bf16x8 (&qf)[8], f32x16 (&O)[4], float& accp,
;                  const int l31, const int hh) {
;   f32x16 z;
;   for (int g = 0; g < 16; ++g) z[g] = 0.f;
;   {
;     bf16x8 kf[8];
; #pragma unroll
;     for (int s = 0; s < 8; ++s) kf[s] = *(const bf16x8*)(lk + (ko0 ^ (32 * s)));
;     __builtin_amdgcn_sched_barrier(0);
; #pragma unroll
;     for (int s = 0; s < 8; ++s) z = mfma32(kf[s], qf[s], z);
;   }
;   bf16x8 vf[4][2];
; #pragma unroll
;   for (int d = 0; d < 4; ++d) { vf[d][0] = *(const bf16x8*)(lv + d * 4096 + vo0); vf[d][1] = *(const bf16x8*)(lv + d * 4096 + (vo0 ^ 32)); }
;   __builtin_amdgcn_sched_barrier(0);
;   float be[16], om[16];
; #pragma unroll
;   for (int g = 0; g < 16; ++g) {
;     const float e = __builtin_amdgcn_exp2f(fminf(-z[g], 120.f));
;     be[g] = __builtin_amdgcn_rcpf(1.f + e);
;     om[g] = e * be[g];
;     if (DIAG) { const int kl = (g & 3) + 8 * (g >> 2) + 4 * hh; if (kl >= l31) { be[g] = 0.f; om[g] = 1.f; } }
;   }
;   float gp[4], pp[4], tot[4];
; #pragma unroll
;   for (int q = 0; q < 4; ++q) { gp[q] = (om[4 * q] * om[4 * q + 1]) * (om[4 * q + 2] * om[4 * q + 3]); pp[q] = __shfl_xor(gp[q], 32); tot[q] = gp[q] * pp[q]; }
;   float suf[4];
;   suf[3] = accp; suf[2] = suf[3] * tot[3]; suf[1] = suf[2] * tot[2]; suf[0] = suf[1] * tot[1];
;   accp = suf[0] * tot[0];
;   f32x16 w;
; #pragma unroll
;   for (int q = 0; q < 4; ++q) {
;     float a = suf[q] * (hh == 0 ? pp[q] : 1.f);
;     w[4 * q + 3] = be[4 * q + 3] * a; a *= om[4 * q + 3];
;     w[4 * q + 2] = be[4 * q + 2] * a; a *= om[4 * q + 2];
;     w[4 * q + 1] = be[4 * q + 1] * a; a *= om[4 * q + 1];
;     w[4 * q + 0] = be[4 * q + 0] * a;
;   }
;   const bf16x8 w0 = cvt8<0>(w), w1 = cvt8<1>(w);
; #pragma unroll
;   for (int d = 0; d < 4; ++d) { O[d] = mfma32(vf[d][0], w0, O[d]); O[d] = mfma32(vf[d][1], w1, O[d]); }
	ds_read_b128 v[64:67], v240 offset:8192
	ds_read_b128 v[80:83], v241 offset:8192
	ds_read_b128 v[84:87], v242 offset:8192
	ds_read_b128 v[88:91], v243 offset:8192
	ds_read_b128 v[92:95], v244 offset:8192
	ds_read_b128 v[96:99], v245 offset:8192
	ds_read_b128 v[100:103], v246 offset:8192
	ds_read_b128 v[104:107], v247 offset:8192
	s_waitcnt lgkmcnt(0)
	v_mfma_f32_32x32x16_bf16 v[64:79], v[64:67], v[128:131], 0
	v_mfma_f32_32x32x16_bf16 v[64:79], v[80:83], v[132:135], v[64:79]
	v_mfma_f32_32x32x16_bf16 v[64:79], v[84:87], v[136:139], v[64:79]
	v_mfma_f32_32x32x16_bf16 v[64:79], v[88:91], v[140:143], v[64:79]
	v_mfma_f32_32x32x16_bf16 v[64:79], v[92:95], v[144:147], v[64:79]
	v_mfma_f32_32x32x16_bf16 v[64:79], v[96:99], v[148:151], v[64:79]
	v_mfma_f32_32x32x16_bf16 v[64:79], v[100:103], v[152:155], v[64:79]
	ds_read_b128 v[84:87], v250
	ds_read_b128 v[96:99], v250 offset:4096
	ds_read_b128 v[80:83], v251
	ds_read_b128 v[100:103], v251 offset:4096
	ds_read_b128 v[112:115], v250 offset:8192
	ds_read_b128 v[164:167], v250 offset:12288
	ds_read_b128 v[116:119], v251 offset:8192
	ds_read_b128 v[160:163], v251 offset:12288
	v_mfma_f32_32x32x16_bf16 v[64:79], v[104:107], v[156:159], v[64:79]
	s_nop 11
	v_min_f32_e64 v68, -v68, s32
	v_exp_f32_e32 v90, v68
	v_min_f32_e64 v68, -v69, s32
	v_exp_f32_e32 v91, v68
	v_add_f32_e32 v68, 1.0, v90
	v_min_f32_e64 v73, -v73, s32
	v_add_f32_e32 v69, 1.0, v91
	v_rcp_f32_e32 v68, v68
	v_rcp_f32_e32 v69, v69
	v_exp_f32_e32 v104, v73
	v_min_f32_e64 v73, -v74, s32
	v_min_f32_e64 v74, -v75, s32
	v_min_f32_e64 v72, -v72, s32
	v_min_f32_e64 v75, -v77, s32
	v_min_f32_e64 v77, -v79, s32
	v_and_b32_e32 v79, 64, v219
	v_exp_f32_e32 v72, v72
	v_exp_f32_e32 v105, v74
	v_min_f32_e64 v74, -v76, s32
	v_exp_f32_e32 v76, v75
	v_min_f32_e64 v75, -v78, s32
	v_xor_b32_e32 v78, 32, v219
	v_add_u32_e32 v79, 64, v79
	v_cmp_lt_i32_e32 vcc, v78, v79
	v_pk_mul_f32 v[90:91], v[90:91], v[68:69]
	v_exp_f32_e32 v73, v73
	v_cndmask_b32_e32 v78, v219, v78, vcc
	v_lshlrev_b32_e32 v170, 2, v78
	v_pk_mul_f32 v[78:79], v[90:91], v[90:91] op_sel_hi:[0,1]
	v_add_f32_e32 v78, 1.0, v72
	v_rcp_f32_e32 v108, v78
	v_add_f32_e32 v78, 1.0, v104
	v_rcp_f32_e32 v110, v78
	v_add_f32_e32 v78, 1.0, v73
	v_rcp_f32_e32 v109, v78
	v_add_f32_e32 v78, 1.0, v105
	v_rcp_f32_e32 v111, v78
	v_exp_f32_e32 v74, v74
	v_exp_f32_e32 v75, v75
	v_exp_f32_e32 v77, v77
	v_pk_mul_f32 v[72:73], v[72:73], v[108:109]
	v_pk_mul_f32 v[104:105], v[104:105], v[110:111]
	v_pk_mul_f32 v[120:121], v[72:73], v[104:105]
	v_add_f32_e32 v72, 1.0, v74
	v_rcp_f32_e32 v122, v72
	v_add_f32_e32 v72, 1.0, v76
	v_rcp_f32_e32 v124, v72
	v_add_f32_e32 v72, 1.0, v75
	v_min_f32_e64 v70, -v70, s32
	v_rcp_f32_e32 v123, v72
	v_add_f32_e32 v72, 1.0, v77
	v_exp_f32_e32 v92, v70
	v_rcp_f32_e32 v125, v72
	v_min_f32_e64 v70, -v71, s32
	v_min_f32_e64 v67, -v67, s32
	v_exp_f32_e32 v93, v70
	v_min_f32_e64 v64, -v64, s32
	v_exp_f32_e32 v196, v67
	v_exp_f32_e32 v88, v64
	v_pk_mul_f32 v[74:75], v[74:75], v[122:123]
	v_pk_mul_f32 v[76:77], v[76:77], v[124:125]
	v_add_f32_e32 v70, 1.0, v92
	v_pk_mul_f32 v[126:127], v[74:75], v[76:77]
	v_add_f32_e32 v71, 1.0, v93
	v_mul_f32_e32 v72, v126, v127
	v_add_f32_e32 v67, 1.0, v196
	v_rcp_f32_e32 v70, v70
	v_rcp_f32_e32 v71, v71
	v_pk_mul_f32 v[120:121], v[120:121], v[120:121] op_sel:[0,1] op_sel_hi:[1,0]
	v_mov_b32_e32 v74, v72
	s_nop 1
	v_permlane32_swap_b32_e32 v72, v74
	v_add_f32_e32 v64, 1.0, v88
	v_min_f32_e64 v66, -v66, s32
	v_rcp_f32_e32 v67, v67
	v_mov_b32_e32 v121, v120
	s_nop 1
	v_permlane32_swap_b32_e32 v120, v121
	v_rcp_f32_e32 v64, v64
	v_min_f32_e64 v65, -v65, s32
	v_exp_f32_e32 v94, v66
	v_exp_f32_e32 v169, v65
	v_pk_mul_f32 v[92:93], v[92:93], v[70:71]
	s_waitcnt lgkmcnt(0)
	v_mul_f32_e32 v127, v72, v74
	v_pk_mul_f32 v[106:107], v[92:93], v[92:93] op_sel_hi:[0,1]
	v_mov_b32_e32 v126, v67
	v_add_f32_e32 v66, 1.0, v94
	v_mov_b32_e32 v89, v79
	v_cndmask_b32_e64 v72, 1.0, v121, s[10:11]
	v_mov_b32_e32 v78, v109
	v_mov_b32_e32 v79, v111
	v_mov_b32_e32 v109, v110
	v_pk_mul_f32 v[110:111], v[196:197], v[126:127]
	v_mov_b32_e32 v106, v64
	v_add_f32_e32 v65, 1.0, v169
	v_rcp_f32_e32 v66, v66
	v_mul_f32_e32 v127, v72, v111
	v_pk_mul_f32 v[88:89], v[88:89], v[106:107]
	v_rcp_f32_e32 v65, v65
	v_mul_f32_e32 v126, v105, v127
	v_mov_b32_e32 v105, v89
	s_nop 1
	v_permlane32_swap_b32_e32 v89, v105
	v_mov_b32_e32 v95, v120
	v_mov_b32_e32 v120, v66
	v_mul_f32_e32 v73, v73, v126
	v_pk_mul_f32 v[94:95], v[94:95], v[120:121]
	v_mul_f32_e32 v72, v104, v73
	v_mul_f32_e32 v104, v169, v65
	v_pk_mul_f32 v[120:121], v[94:95], v[110:111]
	s_waitcnt lgkmcnt(0)
	v_pk_mul_f32 v[88:89], v[88:89], v[104:105]
	v_cndmask_b32_e64 v90, 1.0, v105, s[10:11]
	v_pk_mul_f32 v[88:89], v[88:89], v[120:121]
	v_mov_b32_e32 v95, v88
	s_nop 1
	v_permlane32_swap_b32_e32 v88, v95
	v_cndmask_b32_e64 v74, 1.0, v74, s[10:11]
	v_pk_mul_f32 v[78:79], v[78:79], v[126:127]
	v_pk_mul_f32 v[72:73], v[108:109], v[72:73]
	v_cvt_pk_bf16_f32 v209, v78, v79
	s_waitcnt lgkmcnt(0)
	v_mul_f32_e32 v88, v88, v95
	v_mul_f32_e32 v199, v88, v89
	v_cndmask_b32_e64 v88, 1.0, v95, s[10:11]
	v_mul_f32_e32 v89, v88, v89
	v_mul_f32_e32 v88, v110, v89
	v_pk_mul_f32 v[66:67], v[66:67], v[88:89]
	v_mul_f32_e32 v89, v90, v121
	v_mul_f32_e32 v95, v94, v88
	v_mul_f32_e32 v88, v93, v89
	v_mul_f32_e32 v93, v92, v88
	v_mul_f32_e32 v92, v91, v93
	v_mul_f32_e32 v91, v197, v74
	v_mul_f32_e32 v90, v77, v91
	v_mul_f32_e32 v94, v104, v95
	v_mul_f32_e32 v75, v75, v90
	v_pk_mul_f32 v[64:65], v[64:65], v[94:95]
	v_pk_mul_f32 v[68:69], v[68:69], v[92:93]
	v_pk_mul_f32 v[70:71], v[70:71], v[88:89]
	v_mov_b32_e32 v88, v123
	v_mov_b32_e32 v123, v124
	v_mul_f32_e32 v74, v76, v75
	v_pk_mul_f32 v[74:75], v[122:123], v[74:75]
	v_cvt_pk_bf16_f32 v170, v64, v65
	v_cvt_pk_bf16_f32 v171, v66, v67
	v_cvt_pk_bf16_f32 v172, v68, v69
	v_cvt_pk_bf16_f32 v173, v70, v71
	v_cvt_pk_bf16_f32 v208, v72, v73
	v_cvt_pk_bf16_f32 v210, v74, v75
	v_mfma_f32_32x32x16_bf16 v[64:79], v[84:87], v[170:173], v[48:63]
	v_mov_b32_e32 v89, v125
	v_mul_f32_e64 v88, v88, v90
	v_mul_f32_e64 v89, v89, v91
	v_cvt_pk_bf16_f32 v211, v88, v89
	s_nop 1
	v_mfma_f32_32x32x16_bf16 v[64:79], v[80:83], v[208:211], v[64:79]
	v_mfma_f32_32x32x16_bf16 v[80:95], v[96:99], v[170:173], v[32:47]
	v_mfma_f32_32x32x16_bf16 v[80:95], v[100:103], v[208:211], v[80:95]
	v_mfma_f32_32x32x16_bf16 v[96:111], v[112:115], v[170:173], v[16:31]
	v_mfma_f32_32x32x16_bf16 v[96:111], v[116:119], v[208:211], v[96:111]
	v_mfma_f32_32x32x16_bf16 v[112:127], v[164:167], v[170:173], v[0:15]
	v_mfma_f32_32x32x16_bf16 v[112:127], v[160:163], v[208:211], v[112:127]

; DEV f32x16 mfma32(bf16x8 a, bf16x8 b, f32x16 c) { return __builtin_amdgcn_mfma_f32_32x32x16_bf16(a, b, c, 0, 0, 0); }
; template <bool DIAG>
; DEV void sb_tile(const char* lk, const char* lv, const int ko0, const int vo0, const bf16x8 (&qf)[8], f32x16 (&O)[4], float& accp,
;                  const int l31, const int hh) {
;   f32x16 z;
;   for (int g = 0; g < 16; ++g) z[g] = 0.f;
;   {
;     bf16x8 kf[8];
; #pragma unroll
;     for (int s = 0; s < 8; ++s) kf[s] = *(const bf16x8*)(lk + (ko0 ^ (32 * s)));
;     __builtin_amdgcn_sched_barrier(0);
; #pragma unroll
;     for (int s = 0; s < 8; ++s) z = mfma32(kf[s], qf[s], z);
;   }
;   bf16x8 vf[4][2];
; #pragma unroll
;   for (int d = 0; d < 4; ++d) { vf[d][0] = *(const bf16x8*)(lv + d * 4096 + vo0); vf[d][1] = *(const bf16x8*)(lv + d * 4096 + (vo0 ^ 32)); }
;   __builtin_amdgcn_sched_barrier(0);
;   float be[16], om[16];
; #pragma unroll
;   for (int g = 0; g < 16; ++g) {
;     const float e = __builtin_amdgcn_exp2f(fminf(-z[g], 120.f));
;     be[g] = __builtin_amdgcn_rcpf(1.f + e);
;     om[g] = e * be[g];
;     if (DIAG) { const int kl = (g & 3) + 8 * (g >> 2) + 4 * hh; if (kl >= l31) { be[g] = 0.f; om[g] = 1.f; } }
;   }
;   float gp[4], pp[4], tot[4];
; #pragma unroll
;   for (int q = 0; q < 4; ++q) { gp[q] = (om[4 * q] * om[4 * q + 1]) * (om[4 * q + 2] * om[4 * q + 3]); pp[q] = __shfl_xor(gp[q], 32); tot[q] = gp[q] * pp[q]; }
;   float suf[4];
;   suf[3] = accp; suf[2] = suf[3] * tot[3]; suf[1] = suf[2] * tot[2]; suf[0] = suf[1] * tot[1];
;   accp = suf[0] * tot[0];
;   f32x16 w;
; #pragma unroll
;   for (int q = 0; q < 4; ++q) {
;     float a = suf[q] * (hh == 0 ? pp[q] : 1.f);
;     w[4 * q + 3] = be[4 * q + 3] * a; a *= om[4 * q + 3];
;     w[4 * q + 2] = be[4 * q + 2] * a; a *= om[4 * q + 2];
;     w[4 * q + 1] = be[4 * q + 1] * a; a *= om[4 * q + 1];
;     w[4 * q + 0] = be[4 * q + 0] * a;
;   }
;   const bf16x8 w0 = cvt8<0>(w), w1 = cvt8<1>(w);
; #pragma unroll
;   for (int d = 0; d < 4; ++d) { O[d] = mfma32(vf[d][0], w0, O[d]); O[d] = mfma32(vf[d][1], w1, O[d]); }
; DEV void sb_block(const Params& p, int item) {
;     ...
;     if (2 * j == qt) sb_tile<true>(lb_, lb_, ko0, vo0, qf, O, accp, l31, hh);
;     else if (2 * j < qt) sb_tile<false>(lb_, lb_, ko0, vo0, qf, O, accp, l31, hh);
.LBB0_1217:
	s_cmp_lg_u32 s88, s69
	s_mov_b64 s[66:67], -1
	s_cbranch_scc0 .LBB0_1221
	s_add_i32 s90, s90, 6
	s_cmp_ge_i32 s90, s76
	s_cbranch_scc1 .Lsb_skip_B1
	ds_read_b128 v[0:3], v240
	ds_read_b128 v[16:19], v241
	ds_read_b128 v[20:23], v242
	ds_read_b128 v[24:27], v243
	ds_read_b128 v[28:31], v244
	ds_read_b128 v[32:35], v245
	ds_read_b128 v[36:39], v246
	ds_read_b128 v[40:43], v247
	s_waitcnt lgkmcnt(0)
	v_mfma_f32_32x32x16_bf16 v[0:15], v[0:3], v[128:131], 0
	v_mfma_f32_32x32x16_bf16 v[0:15], v[16:19], v[132:135], v[0:15]
	v_mfma_f32_32x32x16_bf16 v[0:15], v[20:23], v[136:139], v[0:15]
	v_mfma_f32_32x32x16_bf16 v[0:15], v[24:27], v[140:143], v[0:15]
	v_mfma_f32_32x32x16_bf16 v[0:15], v[28:31], v[144:147], v[0:15]
	v_mfma_f32_32x32x16_bf16 v[0:15], v[32:35], v[148:151], v[0:15]
	ds_read_b128 v[28:31], v248
	ds_read_b128 v[16:19], v248 offset:4096
	ds_read_b128 v[24:27], v249
	ds_read_b128 v[20:23], v249 offset:4096
	ds_read_b128 v[168:171], v248 offset:8192
	ds_read_b128 v[164:167], v248 offset:12288
	ds_read_b128 v[172:175], v249 offset:8192
	ds_read_b128 v[160:163], v249 offset:12288
	v_mfma_f32_32x32x16_bf16 v[0:15], v[36:39], v[152:155], v[0:15]
	v_mfma_f32_32x32x16_bf16 v[0:15], v[40:43], v[156:159], v[0:15]
	s_nop 11
	v_min_f32_e64 v4, -v4, s32
	v_exp_f32_e32 v34, v4
	v_min_f32_e64 v4, -v5, s32
	v_exp_f32_e32 v35, v4
	v_add_f32_e32 v4, 1.0, v34
	v_min_f32_e64 v9, -v9, s32
	v_add_f32_e32 v5, 1.0, v35
	v_rcp_f32_e32 v4, v4
	v_rcp_f32_e32 v5, v5
	v_exp_f32_e32 v40, v9
	v_min_f32_e64 v9, -v10, s32
	v_min_f32_e64 v10, -v11, s32
	v_min_f32_e64 v8, -v8, s32
	v_min_f32_e64 v11, -v13, s32
	v_min_f32_e64 v13, -v15, s32
	v_and_b32_e32 v15, 64, v219
	v_exp_f32_e32 v8, v8
	v_exp_f32_e32 v41, v10
	v_min_f32_e64 v10, -v12, s32
	v_exp_f32_e32 v12, v11
	v_min_f32_e64 v11, -v14, s32
	v_xor_b32_e32 v14, 32, v219
	v_add_u32_e32 v15, 64, v15
	v_cmp_lt_i32_e32 vcc, v14, v15
	v_pk_mul_f32 v[34:35], v[34:35], v[4:5]
	v_exp_f32_e32 v9, v9
	v_cndmask_b32_e32 v14, v219, v14, vcc
	v_lshlrev_b32_e32 v57, 2, v14
	v_pk_mul_f32 v[14:15], v[34:35], v[34:35] op_sel_hi:[0,1]
	v_add_f32_e32 v14, 1.0, v8
	v_rcp_f32_e32 v44, v14
	v_add_f32_e32 v14, 1.0, v40
	v_rcp_f32_e32 v46, v14
	v_add_f32_e32 v14, 1.0, v9
	v_rcp_f32_e32 v45, v14
	v_add_f32_e32 v14, 1.0, v41
	v_rcp_f32_e32 v47, v14
	v_exp_f32_e32 v10, v10
	v_exp_f32_e32 v11, v11
	v_exp_f32_e32 v13, v13
	v_pk_mul_f32 v[8:9], v[8:9], v[44:45]
	v_pk_mul_f32 v[40:41], v[40:41], v[46:47]
	v_pk_mul_f32 v[48:49], v[8:9], v[40:41]
	v_add_f32_e32 v8, 1.0, v10
	v_rcp_f32_e32 v50, v8
	v_add_f32_e32 v8, 1.0, v12
	v_rcp_f32_e32 v52, v8
	v_add_f32_e32 v8, 1.0, v11
	v_min_f32_e64 v6, -v6, s32
	v_rcp_f32_e32 v51, v8
	v_add_f32_e32 v8, 1.0, v13
	v_exp_f32_e32 v36, v6
	v_rcp_f32_e32 v53, v8
	v_min_f32_e64 v6, -v7, s32
	v_min_f32_e64 v3, -v3, s32
	v_exp_f32_e32 v37, v6
	v_min_f32_e64 v0, -v0, s32
	v_exp_f32_e32 v198, v3
	v_exp_f32_e32 v32, v0
	v_pk_mul_f32 v[10:11], v[10:11], v[50:51]
	v_pk_mul_f32 v[12:13], v[12:13], v[52:53]
	v_add_f32_e32 v6, 1.0, v36
	v_pk_mul_f32 v[54:55], v[10:11], v[12:13]
	v_add_f32_e32 v7, 1.0, v37
	v_mul_f32_e32 v8, v54, v55
	v_add_f32_e32 v3, 1.0, v198
	v_rcp_f32_e32 v6, v6
	v_rcp_f32_e32 v7, v7
	v_pk_mul_f32 v[48:49], v[48:49], v[48:49] op_sel:[0,1] op_sel_hi:[1,0]
	v_mov_b32_e32 v10, v8
	s_nop 1
	v_permlane32_swap_b32_e32 v8, v10
	v_add_f32_e32 v0, 1.0, v32
	v_min_f32_e64 v2, -v2, s32
	v_rcp_f32_e32 v3, v3
	v_mov_b32_e32 v49, v48
	s_nop 1
	v_permlane32_swap_b32_e32 v48, v49
	v_rcp_f32_e32 v0, v0
	v_min_f32_e64 v1, -v1, s32
	v_exp_f32_e32 v38, v2
	v_exp_f32_e32 v56, v1
	v_pk_mul_f32 v[36:37], v[36:37], v[6:7]
	s_waitcnt lgkmcnt(0)
	v_mul_f32_e32 v55, v8, v10
	v_pk_mul_f32 v[42:43], v[36:37], v[36:37] op_sel_hi:[0,1]
	v_mov_b32_e32 v54, v3
	v_add_f32_e32 v2, 1.0, v38
	v_mov_b32_e32 v33, v15
	v_cndmask_b32_e64 v8, 1.0, v49, s[10:11]
	v_mov_b32_e32 v14, v45
	v_mov_b32_e32 v15, v47
	v_mov_b32_e32 v45, v46
	v_pk_mul_f32 v[46:47], v[198:199], v[54:55]
	v_mov_b32_e32 v42, v0
	v_add_f32_e32 v1, 1.0, v56
	v_rcp_f32_e32 v2, v2
	v_mul_f32_e32 v55, v8, v47
	v_pk_mul_f32 v[32:33], v[32:33], v[42:43]
	v_rcp_f32_e32 v1, v1
	v_mul_f32_e32 v54, v41, v55
	v_mov_b32_e32 v41, v33
	s_nop 1
	v_permlane32_swap_b32_e32 v33, v41
	v_mov_b32_e32 v39, v48
	v_mov_b32_e32 v48, v2
	v_mul_f32_e32 v9, v9, v54
	v_pk_mul_f32 v[38:39], v[38:39], v[48:49]
	v_mul_f32_e32 v8, v40, v9
	v_mul_f32_e32 v40, v56, v1
	v_pk_mul_f32 v[48:49], v[38:39], v[46:47]
	s_waitcnt lgkmcnt(0)
	v_pk_mul_f32 v[32:33], v[32:33], v[40:41]
	v_cndmask_b32_e64 v34, 1.0, v41, s[10:11]
	v_pk_mul_f32 v[32:33], v[32:33], v[48:49]
	v_mov_b32_e32 v39, v32
	s_nop 1
	v_permlane32_swap_b32_e32 v32, v39
	v_cndmask_b32_e64 v10, 1.0, v10, s[10:11]
	v_pk_mul_f32 v[14:15], v[14:15], v[54:55]
	v_pk_mul_f32 v[8:9], v[44:45], v[8:9]
	v_cvt_pk_bf16_f32 v225, v14, v15
	s_waitcnt lgkmcnt(0)
	v_mul_f32_e32 v32, v32, v39
	v_mul_f32_e32 v197, v32, v33
	v_cndmask_b32_e64 v32, 1.0, v39, s[10:11]
	v_mul_f32_e32 v33, v32, v33
	v_mul_f32_e32 v32, v46, v33
	v_pk_mul_f32 v[2:3], v[2:3], v[32:33]
	v_mul_f32_e32 v33, v34, v49
	v_mul_f32_e32 v39, v38, v32
	v_mul_f32_e32 v32, v37, v33
	v_mul_f32_e32 v37, v36, v32
	v_mul_f32_e32 v36, v35, v37
	v_mul_f32_e32 v35, v199, v10
	v_mul_f32_e32 v38, v40, v39
	v_mul_f32_e32 v34, v13, v35
	v_pk_mul_f32 v[0:1], v[0:1], v[38:39]
	v_pk_mul_f32 v[4:5], v[4:5], v[36:37]
	v_pk_mul_f32 v[6:7], v[6:7], v[32:33]
	v_mov_b32_e32 v32, v51
	v_mov_b32_e32 v33, v53
	v_mul_f32_e32 v11, v11, v34
	v_pk_mul_f32 v[32:33], v[32:33], v[34:35]
	v_mov_b32_e32 v51, v52
	v_mul_f32_e32 v10, v12, v11
	v_cvt_pk_bf16_f32 v214, v0, v1
	v_cvt_pk_bf16_f32 v215, v2, v3
	v_cvt_pk_bf16_f32 v216, v4, v5
	v_cvt_pk_bf16_f32 v217, v6, v7
	v_pk_mul_f32 v[10:11], v[50:51], v[10:11]
	v_cvt_pk_bf16_f32 v227, v32, v33
	v_mfma_f32_32x32x16_bf16 v[48:63], v[28:31], v[214:217], v[64:79]
	v_cvt_pk_bf16_f32 v224, v8, v9
	v_cvt_pk_bf16_f32 v226, v10, v11
	v_mfma_f32_32x32x16_bf16 v[32:47], v[16:19], v[214:217], v[80:95]
	s_nop 0
	v_mfma_f32_32x32x16_bf16 v[48:63], v[24:27], v[224:227], v[48:63]
	v_mfma_f32_32x32x16_bf16 v[32:47], v[20:23], v[224:227], v[32:47]
	v_mfma_f32_32x32x16_bf16 v[16:31], v[168:171], v[214:217], v[96:111]
	v_mfma_f32_32x32x16_bf16 v[0:15], v[164:167], v[214:217], v[112:127]
	v_mfma_f32_32x32x16_bf16 v[16:31], v[172:175], v[224:227], v[16:31]
	v_mfma_f32_32x32x16_bf16 v[0:15], v[160:163], v[224:227], v[0:15]
